# mla_fin: s_setprio 1 on the heavier kv-item waves (wave priority strategy), priority reset at the loop tail
# baseline (speedup 1.0000x reference)
; DI unsigned cvtpk(float lo, float hi) { f32x2_t v = {lo, hi}; bf16x2_t b = __builtin_convertvector(v, bf16x2_t); return __builtin_bit_cast(unsigned, b); }
; DI void phase_mla_fin(ArgsP a, int tb_, int l, char* shm, int vcu, int G) {
;     ...
;     for (int it = gw; it < (M / 8) * 2; it += NGW) {
;         const int m = (it >> 1) * 8 + (lane >> 3), h = lane & 7;
;         const bool lat = m < ML; const int t = lat ? (m & 4095) : ((m - ML) & 255); const int b = lat ? (m >> 12) : ((m - ML) >> 8); const int pos = lat ? LC + t : t;
;         const size_t bh = (size_t)(b * 8 + h);
;         const f32x4* rp = (const f32x4*)((const float*)(a->ws + WS_ROPE) + (size_t)(lat ? t : 0) * 32);
;         f32x4 rc[4], rs[4];
; #pragma unroll
;         for (int i = 0; i < 4; ++i) { rc[i] = rp[i]; rs[i] = rp[4 + i]; }
;         if (!(it & 1)) {
;             const u32x4* ps = (const u32x4*)(zcq + (size_t)m * 256) + 4 * h; const u32x4* p = (const u32x4*)(qraw + (size_t)m * 768 + h * 96);
;             u32x4 st[4], w[12];
; #pragma unroll
;             for (int i = 0; i < 4; ++i) st[i] = ps[i];
; #pragma unroll
;             for (int i = 0; i < 12; ++i) w[i] = p[i];
;             const float* gqn = gqn0; asm volatile("" : "+s"(gqn));
;             float cs[16], sn[16];
; #pragma unroll
;             for (int i = 0; i < 4; ++i) { cs[4 * i] = lat ? rc[i].x : 1.f; cs[4 * i + 1] = lat ? rc[i].y : 1.f; cs[4 * i + 2] = lat ? rc[i].z : 1.f; cs[4 * i + 3] = lat ? rc[i].w : 1.f;
;                 sn[4 * i] = lat ? rs[i].x : 0.f; sn[4 * i + 1] = lat ? rs[i].y : 0.f; sn[4 * i + 2] = lat ? rs[i].z : 0.f; sn[4 * i + 3] = lat ? rs[i].w : 0.f; }
;             float ssq = 0.f, ss = 0.f;
; #pragma unroll
;             for (int i = 0; i < 4; ++i) SSQ8(st[i], ssq);
;             ssq += shx(ssq, 1, lane); ssq += shx(ssq, 2, lane); ssq += shx(ssq, 4, lane);
;             const float rq = rsqrtf(ssq * (1.f / 256.f) + EPS);
; #pragma unroll
;             for (int i = 0; i < 12; ++i) SSQ8(w[i], ss);
;             const float rn = rsqrtf(ss * rq * rq * (1.f / 96.f) + EPS) * rq;
;             u32x4* o = (u32x4*)(Qb + (bh * KVLEN + pos) * 96);
; #pragma unroll
;             for (int i = 0; i < 8; ++i) { UNPK(w[i], e); const float sc = rn * C2; u32x4 ow;
;                 ow.x = cvtpk(e[0] * sc * gqn[8 * i], e[1] * sc * gqn[8 * i + 1]); ow.y = cvtpk(e[2] * sc * gqn[8 * i + 2], e[3] * sc * gqn[8 * i + 3]);
.LBB0_964:
	s_or_b64 exec, exec, s[30:31]
	s_setprio 0
	s_waitcnt lgkmcnt(0)
	v_cvt_pk_bf16_f32 v0, v58, v59
	v_cvt_pk_bf16_f32 v1, v34, v35
	v_cvt_pk_bf16_f32 v2, v76, v77
	v_cvt_pk_bf16_f32 v3, v38, v39
	global_store_dwordx4 v[68:69], v[0:3], off offset:128
	v_add_u32_e32 v168, s27, v168
	s_movk_i32 s0, 0x21ff
	v_cvt_pk_bf16_f32 v0, v64, v65
	v_cvt_pk_bf16_f32 v1, v74, v75
	v_cvt_pk_bf16_f32 v2, v78, v79
	v_cvt_pk_bf16_f32 v3, v80, v81
	global_store_dwordx4 v[68:69], v[0:3], off offset:144
	v_cmp_lt_i32_e64 s[6:7], s0, v168
	s_or_b64 s[28:29], s[6:7], s[28:29]
	v_cvt_pk_bf16_f32 v0, v36, v37
	v_cvt_pk_bf16_f32 v1, v32, v33
	v_cvt_pk_bf16_f32 v2, v44, v45
	v_cvt_pk_bf16_f32 v3, v50, v51
	global_store_dwordx4 v[68:69], v[0:3], off offset:160
	v_add_u32_e32 v174, s36, v174
	s_nop 0
	v_cvt_pk_bf16_f32 v0, v66, v67
	v_cvt_pk_bf16_f32 v1, v42, v43
	v_cvt_pk_bf16_f32 v2, v48, v49
	v_cvt_pk_bf16_f32 v3, v40, v41
	global_store_dwordx4 v[68:69], v[0:3], off offset:176
	s_andn2_b64 exec, exec, s[28:29]
	s_cbranch_execz .LBB0_969
.LBB0_965:
	v_and_b32_e32 v0, -8, v174
	v_or_b32_e32 v46, v0, v169
	v_cmp_gt_i32_e64 s[6:7], s74, v46
	v_add_u32_e32 v34, 0xffff8000, v174
	v_ashrrev_i32_e32 v33, 10, v168
	v_cndmask_b32_e64 v1, v238, v239, s[6:7]
	v_bitop3_b32 v32, v1, v0, v169 bitop3:0xe0
	v_lshlrev_b32_e32 v0, 5, v32
	v_cndmask_b32_e64 v0, 0, v0, s[6:7]
	v_lshlrev_b32_e32 v28, 2, v0
	global_load_dwordx4 v[0:3], v28, s[12:13] offset:48
	global_load_dwordx4 v[8:11], v28, s[12:13] offset:32
	global_load_dwordx4 v[16:19], v28, s[12:13] offset:16
	global_load_dwordx4 v[24:27], v28, s[12:13]
	global_load_dwordx4 v[4:7], v28, s[12:13] offset:112
	global_load_dwordx4 v[12:15], v28, s[12:13] offset:96
	global_load_dwordx4 v[20:23], v28, s[12:13] offset:80
	s_nop 0
	global_load_dwordx4 v[28:31], v28, s[12:13] offset:64
	v_lshrrev_b32_e32 v34, 8, v34
	v_cndmask_b32_e64 v33, v34, v33, s[6:7]
	v_add_u32_e32 v34, 0x100, v32
	v_ashrrev_i32_e32 v47, 31, v46
	v_lshl_or_b32 v142, v33, 3, v170
	v_cndmask_b32_e64 v188, v32, v34, s[6:7]
	v_lshlrev_b64 v[52:53], 9, v[46:47]
	s_and_saveexec_b64 s[4:5], vcc
	s_xor_b64 s[30:31], exec, s[4:5]
	s_cbranch_execz .LBB0_967
	s_setprio 1
	v_lshl_add_u64 v[32:33], s[14:15], 0, v[52:53]
	v_mov_b32_e32 v119, v189
	v_lshl_add_u64 v[36:37], v[32:33], 0, v[118:119]
	global_load_dwordx4 v[120:123], v[36:37], off
	global_load_dwordx4 v[124:127], v[36:37], off offset:16
	global_load_dwordx4 v[48:51], v[32:33], off offset:304
	global_load_dwordx4 v[52:55], v[32:33], off offset:288
	global_load_dwordx4 v[56:59], v[32:33], off offset:272
	global_load_dwordx4 v[60:63], v[32:33], off offset:256
	v_lshlrev_b64 v[34:35], 11, v[46:47]
	v_lshl_add_u64 v[92:93], v[112:113], 0, v[34:35]
	global_load_dwordx4 v[40:43], v[92:93], off offset:16
	global_load_dwordx4 v[44:47], v[92:93], off
	global_load_dwordx4 v[68:71], v[92:93], off offset:48
	global_load_dwordx4 v[76:79], v[92:93], off offset:32
	global_load_dwordx4 v[96:99], v[92:93], off offset:176
	global_load_dwordx4 v[100:103], v[92:93], off offset:160
	global_load_dwordx4 v[104:107], v[92:93], off offset:144
	global_load_dwordx4 v[108:111], v[92:93], off offset:128
	global_load_dwordx4 v[32:35], v[92:93], off offset:112
	global_load_dwordx4 v[36:39], v[92:93], off offset:96
	global_load_dwordx4 v[64:67], v[92:93], off offset:80
	global_load_dwordx4 v[72:75], v[92:93], off offset:64
	global_load_dwordx4 v[80:83], v[92:93], off offset:240
	global_load_dwordx4 v[84:87], v[92:93], off offset:224
	global_load_dwordx4 v[88:91], v[92:93], off offset:208
	s_nop 0
	global_load_dwordx4 v[92:95], v[92:93], off offset:192
	s_mov_b32 s2, 0x88000
	s_mov_b64 s[34:35], s[24:25]
	s_waitcnt vmcnt(0)
	v_cndmask_b32_e64 v25, 1.0, v25, s[6:7]
	v_cndmask_b32_e64 v24, 1.0, v24, s[6:7]
	v_cndmask_b32_e64 v29, 0, v29, s[6:7]
	v_cndmask_b32_e64 v28, 0, v28, s[6:7]
	v_cndmask_b32_e64 v27, 1.0, v27, s[6:7]
	v_cndmask_b32_e64 v26, 1.0, v26, s[6:7]
	v_cndmask_b32_e64 v31, 0, v31, s[6:7]
	v_cndmask_b32_e64 v30, 0, v30, s[6:7]
	v_cndmask_b32_e64 v17, 1.0, v17, s[6:7]
	v_cndmask_b32_e64 v16, 1.0, v16, s[6:7]
	v_cndmask_b32_e64 v21, 0, v21, s[6:7]
	v_cndmask_b32_e64 v20, 0, v20, s[6:7]
	v_cndmask_b32_e64 v19, 1.0, v19, s[6:7]
	v_cndmask_b32_e64 v18, 1.0, v18, s[6:7]
	v_cndmask_b32_e64 v23, 0, v23, s[6:7]
	v_cndmask_b32_e64 v22, 0, v22, s[6:7]
	v_cndmask_b32_e64 v9, 1.0, v9, s[6:7]
	v_cndmask_b32_e64 v8, 1.0, v8, s[6:7]
	v_cndmask_b32_e64 v13, 0, v13, s[6:7]
	v_cndmask_b32_e64 v12, 0, v12, s[6:7]
	v_cndmask_b32_e64 v11, 1.0, v11, s[6:7]
	v_cndmask_b32_e64 v10, 1.0, v10, s[6:7]
	v_cndmask_b32_e64 v15, 0, v15, s[6:7]
	v_cndmask_b32_e64 v14, 0, v14, s[6:7]
	v_lshlrev_b32_e32 v156, 16, v45
	v_and_b32_e32 v157, 0xffff0000, v45
	v_lshlrev_b32_e32 v158, 16, v44
	v_and_b32_e32 v159, 0xffff0000, v44
	v_lshlrev_b32_e32 v150, 16, v47
	v_and_b32_e32 v151, 0xffff0000, v47
	v_and_b32_e32 v130, 0xffff0000, v120
	v_lshlrev_b32_e32 v129, 16, v124
	v_and_b32_e32 v131, 0xffff0000, v124
	v_lshlrev_b32_e32 v133, 16, v125
	v_and_b32_e32 v125, 0xffff0000, v125
	v_and_b32_e32 v124, 0xffff0000, v121
	v_lshlrev_b32_e32 v128, 16, v120
	v_lshlrev_b32_e32 v132, 16, v121
	v_lshlrev_b32_e32 v121, 16, v126
	v_lshlrev_b32_e32 v120, 16, v122
	v_and_b32_e32 v135, 0xffff0000, v126
	v_and_b32_e32 v134, 0xffff0000, v122
	v_lshlrev_b32_e32 v136, 16, v123
	v_and_b32_e32 v126, 0xffff0000, v123
	v_pk_mul_f32 v[122:123], v[130:131], v[130:131]
	v_pk_mul_f32 v[124:125], v[124:125], v[124:125]
	v_pk_fma_f32 v[122:123], v[128:129], v[128:129], v[122:123]
	v_pk_fma_f32 v[124:125], v[132:133], v[132:133], v[124:125]
	v_lshlrev_b32_e32 v137, 16, v127
	v_pk_add_f32 v[122:123], v[122:123], v[124:125]
	v_pk_mul_f32 v[124:125], v[134:135], v[134:135]
	v_and_b32_e32 v127, 0xffff0000, v127
	v_pk_fma_f32 v[120:121], v[120:121], v[120:121], v[124:125]
	v_and_b32_e32 v124, 0xffff0000, v109
	v_pk_add_f32 v[120:121], v[120:121], v[122:123]
	v_pk_mul_f32 v[122:123], v[126:127], v[126:127]
	v_lshlrev_b32_e32 v125, 16, v110
	v_pk_fma_f32 v[122:123], v[136:137], v[136:137], v[122:123]
	v_and_b32_e32 v110, 0xffff0000, v110
	v_pk_add_f32 v[120:121], v[122:123], v[120:121]
	v_lshlrev_b32_e32 v122, 1, v188
	v_add_f32_e32 v119, v120, v121
	v_mov_b32_e32 v123, v189
	v_lshlrev_b32_e32 v126, 16, v111
	v_and_b32_e32 v111, 0xffff0000, v111
	v_and_b32_e32 v127, 0xffff0000, v68
	s_waitcnt lgkmcnt(0)
; DI bf16_t f2bf(float f) { return (bf16_t)(cvtpk(f, f) & 0xffffu); }
; DI float shx(float v, int mask, int lane) { return __int_as_float(__builtin_amdgcn_ds_bpermute((lane ^ mask) << 2, __float_as_int(v))); }
; #define UNPK(W_, E_) const float E_[8] = {bflo((W_).x), bfhi((W_).x), bflo((W_).y), bfhi((W_).y), bflo((W_).z), bfhi((W_).z), bflo((W_).w), bfhi((W_).w)}
; DI void phase_mla_fin(ArgsP a, int tb_, int l, char* shm, int vcu, int G) {
;     ...
;             sskv += shx(sskv, 1, lane); sskv += shx(sskv, 2, lane); sskv += shx(sskv, 4, lane);
;             const float rkv = rsqrtf(sskv * (1.f / 128.f) + EPS);
;             { bf16_t* vo = Vt + bh * 64 * KVLEN + pos;
; #pragma unroll
;               for (int i = 0; i < 8; ++i) { UNPK(vw[i], e);
; #pragma unroll
;                   for (int j = 0; j < 8; ++j) vo[(size_t)(8 * i + j) * KVLEN] = f2bf(e[j] * rkv); } }
	s_nop 1
	v_add_f32_dpp v119, v119, v119 quad_perm:[1,0,3,2] row_mask:0xf bank_mask:0xf
	v_and_b32_e32 v131, 0xffff0000, v72
	v_and_b32_e32 v130, 0xffff0000, v74
	v_and_b32_e32 v133, 0xffff0000, v64
	v_and_b32_e32 v132, 0xffff0000, v66
	s_waitcnt lgkmcnt(0)
	s_nop 1
	v_add_f32_dpp v119, v119, v119 quad_perm:[2,3,0,1] row_mask:0xf bank_mask:0xf
	v_lshlrev_b32_e32 v154, 16, v46
	v_and_b32_e32 v155, 0xffff0000, v46
	s_waitcnt lgkmcnt(0)
	s_nop 1
	v_add_f32_dpp v119, v119, v119 row_half_mirror row_mask:0xf bank_mask:0xf
	v_fmamk_f32 v119, v119, 0x3c000000, v230
	v_cmp_gt_f32_e64 s[8:9], s76, v119
	v_mul_f32_e32 v120, 0x4b800000, v119
	s_nop 0
	v_cndmask_b32_e64 v119, v119, v120, s[8:9]
	v_rsq_f32_e32 v119, v119
	s_nop 0
	v_mul_f32_e32 v120, 0x45800000, v119
	v_cndmask_b32_e64 v119, v119, v120, s[8:9]
	v_mov_b64_e32 v[120:121], s[20:21]
	v_mad_i64_i32 v[120:121], s[4:5], v142, s2, v[120:121]
	v_lshl_add_u64 v[120:121], v[120:121], 0, v[122:123]
	v_lshlrev_b32_e32 v122, 16, v108
	v_and_b32_e32 v108, 0xffff0000, v108
	v_lshlrev_b32_e32 v123, 16, v109
	v_mul_f32_e32 v109, v119, v122
	v_mul_f32_e32 v108, v119, v108
	s_movk_i32 s2, 0x2000
	v_cvt_pk_bf16_f32 v109, v109, s0
	v_cvt_pk_bf16_f32 v122, v108, s0
	v_add_co_u32_e64 v108, s[8:9], s2, v120
	global_store_short v[120:121], v109, off
	s_nop 0
	v_addc_co_u32_e64 v109, s[8:9], 0, v121, s[8:9]
	global_store_short v[108:109], v122, off offset:512
	v_mul_f32_e32 v108, v119, v123
	v_cvt_pk_bf16_f32 v122, v108, s0
	s_movk_i32 s0, 0x4000
	v_add_co_u32_e64 v108, s[8:9], s0, v120
	s_movk_i32 s2, 0x6000
	s_nop 0
	v_addc_co_u32_e64 v109, s[8:9], 0, v121, s[8:9]
	global_store_short v[108:109], v122, off offset:1024
	v_mul_f32_e32 v108, v119, v124
	v_cvt_pk_bf16_f32 v122, v108, s0
	v_add_co_u32_e64 v108, s[8:9], s2, v120
	s_mov_b32 s2, 0xa000
	s_nop 0
	v_addc_co_u32_e64 v109, s[8:9], 0, v121, s[8:9]
	global_store_short v[108:109], v122, off offset:1536
	v_mul_f32_e32 v108, v119, v125
	v_cvt_pk_bf16_f32 v122, v108, s0
	v_add_co_u32_e64 v108, s[8:9], s74, v120
	v_lshlrev_b32_e32 v123, 16, v107
	s_nop 0
	v_addc_co_u32_e64 v109, s[8:9], 0, v121, s[8:9]
	global_store_short v[108:109], v122, off offset:2048
	v_mul_f32_e32 v108, v119, v110
	v_cvt_pk_bf16_f32 v110, v108, s0
	v_add_co_u32_e64 v108, s[8:9], s2, v120
	s_mov_b32 s2, 0xe000
	s_nop 0
	v_addc_co_u32_e64 v109, s[8:9], 0, v121, s[8:9]
	global_store_short v[108:109], v110, off offset:2560
	v_mul_f32_e32 v108, v119, v126
	v_cvt_pk_bf16_f32 v110, v108, s0
	s_mov_b32 s0, 0xc000
	v_add_co_u32_e64 v108, s[8:9], s0, v120
	v_lshlrev_b32_e32 v122, 16, v106
	s_nop 0
	v_addc_co_u32_e64 v109, s[8:9], 0, v121, s[8:9]
	global_store_short v[108:109], v110, off offset:3072
	v_mul_f32_e32 v108, v119, v111
	v_cvt_pk_bf16_f32 v110, v108, s0
	v_add_co_u32_e64 v108, s[8:9], s2, v120
	s_mov_b32 s2, 0x11000
	s_nop 0
	v_addc_co_u32_e64 v109, s[8:9], 0, v121, s[8:9]
	global_store_short v[108:109], v110, off offset:3584
	v_lshlrev_b32_e32 v108, 16, v104
	v_and_b32_e32 v109, 0xffff0000, v104
	v_mul_f32_e32 v104, v119, v108
	v_cvt_pk_bf16_f32 v108, v104, s0
	v_add_co_u32_e64 v104, s[8:9], s2, v120
	v_lshlrev_b32_e32 v110, 16, v105
	v_and_b32_e32 v111, 0xffff0000, v105
	v_addc_co_u32_e64 v105, s[8:9], 0, v121, s[8:9]
	global_store_short v[104:105], v108, off
	v_mul_f32_e32 v104, v119, v109
	s_mov_b32 s2, 0x13000
	v_cvt_pk_bf16_f32 v108, v104, s0
	v_add_co_u32_e64 v104, s[8:9], s2, v120
	s_mov_b32 s2, 0x15000
	s_nop 0
	v_addc_co_u32_e64 v105, s[8:9], 0, v121, s[8:9]
	global_store_short v[104:105], v108, off offset:512
	v_mul_f32_e32 v104, v119, v110
	v_cvt_pk_bf16_f32 v108, v104, s0
	v_add_co_u32_e64 v104, s[8:9], s2, v120
	s_mov_b32 s2, 0x17000
	s_nop 0
	v_addc_co_u32_e64 v105, s[8:9], 0, v121, s[8:9]
	global_store_short v[104:105], v108, off offset:1024
	v_mul_f32_e32 v104, v119, v111
	v_cvt_pk_bf16_f32 v108, v104, s0
	v_add_co_u32_e64 v104, s[8:9], s2, v120
	s_mov_b32 s2, 0x19000
	s_nop 0
	v_addc_co_u32_e64 v105, s[8:9], 0, v121, s[8:9]
	global_store_short v[104:105], v108, off offset:1536
	v_mul_f32_e32 v104, v119, v122
	v_cvt_pk_bf16_f32 v108, v104, s0
	v_add_co_u32_e64 v104, s[8:9], s2, v120
	v_and_b32_e32 v106, 0xffff0000, v106
	s_nop 0
	v_addc_co_u32_e64 v105, s[8:9], 0, v121, s[8:9]
	global_store_short v[104:105], v108, off offset:2048
	v_mul_f32_e32 v104, v119, v106
	v_cvt_pk_bf16_f32 v106, v104, s0
	v_add_co_u32_e64 v104, s[8:9], s56, v120
	s_mov_b32 s2, 0x1d000
	s_nop 0
	v_addc_co_u32_e64 v105, s[8:9], 0, v121, s[8:9]
	global_store_short v[104:105], v106, off offset:2560
	v_mul_f32_e32 v104, v119, v123
	v_cvt_pk_bf16_f32 v106, v104, s0
	v_add_co_u32_e64 v104, s[8:9], s2, v120
	v_and_b32_e32 v107, 0xffff0000, v107
	s_nop 0
	v_addc_co_u32_e64 v105, s[8:9], 0, v121, s[8:9]
	global_store_short v[104:105], v106, off offset:3072
	v_mul_f32_e32 v104, v119, v107
	s_mov_b32 s2, 0x1f000
	v_cvt_pk_bf16_f32 v106, v104, s0
	v_add_co_u32_e64 v104, s[8:9], s2, v120
	s_mov_b32 s2, 0x22000
	s_nop 0
	v_addc_co_u32_e64 v105, s[8:9], 0, v121, s[8:9]
	global_store_short v[104:105], v106, off offset:3584
	v_lshlrev_b32_e32 v104, 16, v100
	v_and_b32_e32 v105, 0xffff0000, v100
	v_mul_f32_e32 v100, v119, v104
	v_cvt_pk_bf16_f32 v104, v100, s0
	v_add_co_u32_e64 v100, s[8:9], s2, v120
	v_lshlrev_b32_e32 v106, 16, v101
	v_and_b32_e32 v107, 0xffff0000, v101
	v_addc_co_u32_e64 v101, s[8:9], 0, v121, s[8:9]
	global_store_short v[100:101], v104, off
	v_mul_f32_e32 v100, v119, v105
	v_cvt_pk_bf16_f32 v104, v100, s0
	s_mov_b32 s0, 0x24000
	v_add_co_u32_e64 v100, s[8:9], s0, v120
	s_mov_b32 s2, 0x26000
	s_nop 0
	v_addc_co_u32_e64 v101, s[8:9], 0, v121, s[8:9]
	global_store_short v[100:101], v104, off offset:512
; DI bf16_t f2bf(float f) { return (bf16_t)(cvtpk(f, f) & 0xffffu); }
; #define UNPK(W_, E_) const float E_[8] = {bflo((W_).x), bfhi((W_).x), bflo((W_).y), bfhi((W_).y), bflo((W_).z), bfhi((W_).z), bflo((W_).w), bfhi((W_).w)}
; DI void phase_mla_fin(ArgsP a, int tb_, int l, char* shm, int vcu, int G) {
;     ...
;             { bf16_t* vo = Vt + bh * 64 * KVLEN + pos;
; #pragma unroll
;               for (int i = 0; i < 8; ++i) { UNPK(vw[i], e);
; #pragma unroll
;                   for (int j = 0; j < 8; ++j) vo[(size_t)(8 * i + j) * KVLEN] = f2bf(e[j] * rkv); } }
	v_mul_f32_e32 v100, v119, v106
	v_cvt_pk_bf16_f32 v104, v100, s0
	v_add_co_u32_e64 v100, s[8:9], s2, v120
	v_lshlrev_b32_e32 v108, 16, v102
	s_nop 0
	v_addc_co_u32_e64 v101, s[8:9], 0, v121, s[8:9]
	global_store_short v[100:101], v104, off offset:1024
	v_mul_f32_e32 v100, v119, v107
	v_cvt_pk_bf16_f32 v104, v100, s0
	s_mov_b32 s0, 0x28000
	v_add_co_u32_e64 v100, s[8:9], s0, v120
	s_mov_b32 s2, 0x2a000
	s_nop 0
	v_addc_co_u32_e64 v101, s[8:9], 0, v121, s[8:9]
	global_store_short v[100:101], v104, off offset:1536
	v_mul_f32_e32 v100, v119, v108
	v_cvt_pk_bf16_f32 v104, v100, s0
	v_add_co_u32_e64 v100, s[8:9], s2, v120
	v_and_b32_e32 v102, 0xffff0000, v102
	s_nop 0
	v_addc_co_u32_e64 v101, s[8:9], 0, v121, s[8:9]
	global_store_short v[100:101], v104, off offset:2048
	v_mul_f32_e32 v100, v119, v102
	v_cvt_pk_bf16_f32 v102, v100, s0
	s_mov_b32 s0, 0x2c000
	v_add_co_u32_e64 v100, s[8:9], s0, v120
	v_lshlrev_b32_e32 v109, 16, v103
	s_nop 0
	v_addc_co_u32_e64 v101, s[8:9], 0, v121, s[8:9]
	global_store_short v[100:101], v102, off offset:2560
	v_mul_f32_e32 v100, v119, v109
	s_mov_b32 s2, 0x2e000
	v_cvt_pk_bf16_f32 v102, v100, s0
	v_add_co_u32_e64 v100, s[8:9], s2, v120
	v_and_b32_e32 v103, 0xffff0000, v103
	s_nop 0
	v_addc_co_u32_e64 v101, s[8:9], 0, v121, s[8:9]
	global_store_short v[100:101], v102, off offset:3072
	v_mul_f32_e32 v100, v119, v103
	s_mov_b32 s2, 0x30000
	v_cvt_pk_bf16_f32 v102, v100, s0
	v_add_co_u32_e64 v100, s[8:9], s2, v120
	s_mov_b32 s2, 0x33000
	s_nop 0
	v_addc_co_u32_e64 v101, s[8:9], 0, v121, s[8:9]
	global_store_short v[100:101], v102, off offset:3584
	v_lshlrev_b32_e32 v100, 16, v96
	v_and_b32_e32 v101, 0xffff0000, v96
	v_mul_f32_e32 v96, v119, v100
	v_cvt_pk_bf16_f32 v100, v96, s0
	v_add_co_u32_e64 v96, s[8:9], s2, v120
	v_lshlrev_b32_e32 v102, 16, v97
	v_and_b32_e32 v103, 0xffff0000, v97
	v_addc_co_u32_e64 v97, s[8:9], 0, v121, s[8:9]
	global_store_short v[96:97], v100, off
	v_mul_f32_e32 v96, v119, v101
	s_mov_b32 s2, 0x35000
	v_cvt_pk_bf16_f32 v100, v96, s0
	v_add_co_u32_e64 v96, s[8:9], s2, v120
	s_mov_b32 s2, 0x37000
	s_nop 0
	v_addc_co_u32_e64 v97, s[8:9], 0, v121, s[8:9]
	global_store_short v[96:97], v100, off offset:512
	v_mul_f32_e32 v96, v119, v102
	v_cvt_pk_bf16_f32 v100, v96, s0
	v_add_co_u32_e64 v96, s[8:9], s2, v120
	s_mov_b32 s2, 0x39000
	s_nop 0
	v_addc_co_u32_e64 v97, s[8:9], 0, v121, s[8:9]
	global_store_short v[96:97], v100, off offset:1024
	v_mul_f32_e32 v96, v119, v103
	v_cvt_pk_bf16_f32 v100, v96, s0
	v_add_co_u32_e64 v96, s[8:9], s2, v120
	v_lshlrev_b32_e32 v104, 16, v98
	s_nop 0
	v_addc_co_u32_e64 v97, s[8:9], 0, v121, s[8:9]
	global_store_short v[96:97], v100, off offset:1536
	v_mul_f32_e32 v96, v119, v104
	s_mov_b32 s2, 0x3b000
	v_cvt_pk_bf16_f32 v100, v96, s0
	v_add_co_u32_e64 v96, s[8:9], s2, v120
	v_and_b32_e32 v98, 0xffff0000, v98
	s_nop 0
	v_addc_co_u32_e64 v97, s[8:9], 0, v121, s[8:9]
	global_store_short v[96:97], v100, off offset:2048
	v_mul_f32_e32 v96, v119, v98
	s_mov_b32 s2, 0x3d000
	v_cvt_pk_bf16_f32 v98, v96, s0
	v_add_co_u32_e64 v96, s[8:9], s2, v120
	v_lshlrev_b32_e32 v105, 16, v99
	s_nop 0
	v_addc_co_u32_e64 v97, s[8:9], 0, v121, s[8:9]
	global_store_short v[96:97], v98, off offset:2560
	v_mul_f32_e32 v96, v119, v105
	s_mov_b32 s2, 0x3f000
	v_cvt_pk_bf16_f32 v98, v96, s0
	v_add_co_u32_e64 v96, s[8:9], s2, v120
	v_and_b32_e32 v99, 0xffff0000, v99
	s_nop 0
	v_addc_co_u32_e64 v97, s[8:9], 0, v121, s[8:9]
	global_store_short v[96:97], v98, off offset:3072
	v_mul_f32_e32 v96, v119, v99
	s_mov_b32 s2, 0x41000
	v_cvt_pk_bf16_f32 v98, v96, s0
	v_add_co_u32_e64 v96, s[8:9], s2, v120
	s_mov_b32 s2, 0x44000
	s_nop 0
	v_addc_co_u32_e64 v97, s[8:9], 0, v121, s[8:9]
	global_store_short v[96:97], v98, off offset:3584
	v_lshlrev_b32_e32 v96, 16, v92
	v_and_b32_e32 v97, 0xffff0000, v92
	v_mul_f32_e32 v92, v119, v96
	v_cvt_pk_bf16_f32 v96, v92, s0
	v_add_co_u32_e64 v92, s[8:9], s2, v120
	v_lshlrev_b32_e32 v98, 16, v93
	v_and_b32_e32 v99, 0xffff0000, v93
	v_addc_co_u32_e64 v93, s[8:9], 0, v121, s[8:9]
	global_store_short v[92:93], v96, off
	v_mul_f32_e32 v92, v119, v97
	s_mov_b32 s2, 0x46000
	v_cvt_pk_bf16_f32 v96, v92, s0
	v_add_co_u32_e64 v92, s[8:9], s2, v120
	s_mov_b32 s2, 0x4a000
	s_nop 0
	v_addc_co_u32_e64 v93, s[8:9], 0, v121, s[8:9]
	global_store_short v[92:93], v96, off offset:512
	v_mul_f32_e32 v92, v119, v98
	v_cvt_pk_bf16_f32 v96, v92, s0
	s_mov_b32 s0, 0x48000
	v_add_co_u32_e64 v92, s[8:9], s0, v120
	v_lshlrev_b32_e32 v100, 16, v94
	s_nop 0
	v_addc_co_u32_e64 v93, s[8:9], 0, v121, s[8:9]
	global_store_short v[92:93], v96, off offset:1024
	v_mul_f32_e32 v92, v119, v99
	v_cvt_pk_bf16_f32 v96, v92, s0
	v_add_co_u32_e64 v92, s[8:9], s2, v120
	s_mov_b32 s2, 0x4c000
	s_nop 0
	v_addc_co_u32_e64 v93, s[8:9], 0, v121, s[8:9]
	global_store_short v[92:93], v96, off offset:1536
	v_mul_f32_e32 v92, v119, v100
	v_cvt_pk_bf16_f32 v96, v92, s0
	v_add_co_u32_e64 v92, s[8:9], s2, v120
	v_and_b32_e32 v94, 0xffff0000, v94
	s_nop 0
	v_addc_co_u32_e64 v93, s[8:9], 0, v121, s[8:9]
	global_store_short v[92:93], v96, off offset:2048
	v_mul_f32_e32 v92, v119, v94
	s_mov_b32 s2, 0x4e000
	v_cvt_pk_bf16_f32 v94, v92, s0
	v_add_co_u32_e64 v92, s[8:9], s2, v120
	v_lshlrev_b32_e32 v101, 16, v95
	s_nop 0
	v_addc_co_u32_e64 v93, s[8:9], 0, v121, s[8:9]
	global_store_short v[92:93], v94, off offset:2560
	v_mul_f32_e32 v92, v119, v101
	v_cvt_pk_bf16_f32 v94, v92, s0
	s_mov_b32 s0, 0x50000
	v_add_co_u32_e64 v92, s[8:9], s0, v120
	v_and_b32_e32 v95, 0xffff0000, v95
	s_nop 0
	v_addc_co_u32_e64 v93, s[8:9], 0, v121, s[8:9]
	global_store_short v[92:93], v94, off offset:3072
	v_mul_f32_e32 v92, v119, v95
	s_mov_b32 s2, 0x52000
; DI bf16_t f2bf(float f) { return (bf16_t)(cvtpk(f, f) & 0xffffu); }
; #define UNPK(W_, E_) const float E_[8] = {bflo((W_).x), bfhi((W_).x), bflo((W_).y), bfhi((W_).y), bflo((W_).z), bfhi((W_).z), bflo((W_).w), bfhi((W_).w)}
; DI void phase_mla_fin(ArgsP a, int tb_, int l, char* shm, int vcu, int G) {
;     ...
;             { bf16_t* vo = Vt + bh * 64 * KVLEN + pos;
; #pragma unroll
;               for (int i = 0; i < 8; ++i) { UNPK(vw[i], e);
; #pragma unroll
;                   for (int j = 0; j < 8; ++j) vo[(size_t)(8 * i + j) * KVLEN] = f2bf(e[j] * rkv); } }
	v_cvt_pk_bf16_f32 v94, v92, s0
	v_add_co_u32_e64 v92, s[8:9], s2, v120
	s_mov_b32 s2, 0x55000
	s_nop 0
	v_addc_co_u32_e64 v93, s[8:9], 0, v121, s[8:9]
	global_store_short v[92:93], v94, off offset:3584
	v_lshlrev_b32_e32 v92, 16, v88
	v_and_b32_e32 v93, 0xffff0000, v88
	v_mul_f32_e32 v88, v119, v92
	v_cvt_pk_bf16_f32 v92, v88, s0
	v_add_co_u32_e64 v88, s[8:9], s2, v120
	v_lshlrev_b32_e32 v94, 16, v89
	v_and_b32_e32 v95, 0xffff0000, v89
	v_addc_co_u32_e64 v89, s[8:9], 0, v121, s[8:9]
	global_store_short v[88:89], v92, off
	v_mul_f32_e32 v88, v119, v93
	s_mov_b32 s2, 0x57000
	v_cvt_pk_bf16_f32 v92, v88, s0
	v_add_co_u32_e64 v88, s[8:9], s2, v120
	s_mov_b32 s2, 0x59000
	s_nop 0
	v_addc_co_u32_e64 v89, s[8:9], 0, v121, s[8:9]
	global_store_short v[88:89], v92, off offset:512
	v_mul_f32_e32 v88, v119, v94
	v_cvt_pk_bf16_f32 v92, v88, s0
	v_add_co_u32_e64 v88, s[8:9], s2, v120
	s_mov_b32 s2, 0x5b000
	s_nop 0
	v_addc_co_u32_e64 v89, s[8:9], 0, v121, s[8:9]
	global_store_short v[88:89], v92, off offset:1024
	v_mul_f32_e32 v88, v119, v95
	v_cvt_pk_bf16_f32 v92, v88, s0
	v_add_co_u32_e64 v88, s[8:9], s2, v120
	v_lshlrev_b32_e32 v96, 16, v90
	s_nop 0
	v_addc_co_u32_e64 v89, s[8:9], 0, v121, s[8:9]
	global_store_short v[88:89], v92, off offset:1536
	v_mul_f32_e32 v88, v119, v96
	s_mov_b32 s2, 0x5d000
	v_cvt_pk_bf16_f32 v92, v88, s0
	v_add_co_u32_e64 v88, s[8:9], s2, v120
	v_and_b32_e32 v90, 0xffff0000, v90
	s_nop 0
	v_addc_co_u32_e64 v89, s[8:9], 0, v121, s[8:9]
	global_store_short v[88:89], v92, off offset:2048
	v_mul_f32_e32 v88, v119, v90
	s_mov_b32 s2, 0x5f000
	v_cvt_pk_bf16_f32 v90, v88, s0
	v_add_co_u32_e64 v88, s[8:9], s2, v120
	v_lshlrev_b32_e32 v97, 16, v91
	s_nop 0
	v_addc_co_u32_e64 v89, s[8:9], 0, v121, s[8:9]
	global_store_short v[88:89], v90, off offset:2560
	v_mul_f32_e32 v88, v119, v97
	s_mov_b32 s2, 0x61000
	v_cvt_pk_bf16_f32 v90, v88, s0
	v_add_co_u32_e64 v88, s[8:9], s2, v120
	v_and_b32_e32 v91, 0xffff0000, v91
	s_nop 0
	v_addc_co_u32_e64 v89, s[8:9], 0, v121, s[8:9]
	global_store_short v[88:89], v90, off offset:3072
	v_mul_f32_e32 v88, v119, v91
	s_mov_b32 s2, 0x63000
	v_cvt_pk_bf16_f32 v90, v88, s0
	v_add_co_u32_e64 v88, s[8:9], s2, v120
	s_mov_b32 s2, 0x66000
	s_nop 0
	v_addc_co_u32_e64 v89, s[8:9], 0, v121, s[8:9]
	global_store_short v[88:89], v90, off offset:3584
	v_lshlrev_b32_e32 v88, 16, v84
	v_and_b32_e32 v89, 0xffff0000, v84
	v_mul_f32_e32 v84, v119, v88
	v_cvt_pk_bf16_f32 v88, v84, s0
	v_add_co_u32_e64 v84, s[8:9], s2, v120
	v_lshlrev_b32_e32 v90, 16, v85
	v_and_b32_e32 v91, 0xffff0000, v85
	v_addc_co_u32_e64 v85, s[8:9], 0, v121, s[8:9]
	global_store_short v[84:85], v88, off
	v_mul_f32_e32 v84, v119, v89
	s_mov_b32 s2, 0x68000
	v_cvt_pk_bf16_f32 v88, v84, s0
	v_add_co_u32_e64 v84, s[8:9], s2, v120
	s_mov_b32 s2, 0x6a000
	s_nop 0
	v_addc_co_u32_e64 v85, s[8:9], 0, v121, s[8:9]
	global_store_short v[84:85], v88, off offset:512
	v_mul_f32_e32 v84, v119, v90
	v_cvt_pk_bf16_f32 v88, v84, s0
	v_add_co_u32_e64 v84, s[8:9], s2, v120
	s_mov_b32 s2, 0x6c000
	s_nop 0
	v_addc_co_u32_e64 v85, s[8:9], 0, v121, s[8:9]
	global_store_short v[84:85], v88, off offset:1024
	v_mul_f32_e32 v84, v119, v91
	v_cvt_pk_bf16_f32 v88, v84, s0
	v_add_co_u32_e64 v84, s[8:9], s2, v120
	v_lshlrev_b32_e32 v92, 16, v86
	s_nop 0
	v_addc_co_u32_e64 v85, s[8:9], 0, v121, s[8:9]
	global_store_short v[84:85], v88, off offset:1536
	v_mul_f32_e32 v84, v119, v92
	s_mov_b32 s2, 0x6e000
	v_cvt_pk_bf16_f32 v88, v84, s0
	v_add_co_u32_e64 v84, s[8:9], s2, v120
	v_and_b32_e32 v86, 0xffff0000, v86
	s_nop 0
	v_addc_co_u32_e64 v85, s[8:9], 0, v121, s[8:9]
	global_store_short v[84:85], v88, off offset:2048
	v_mul_f32_e32 v84, v119, v86
	s_mov_b32 s2, 0x70000
	v_cvt_pk_bf16_f32 v86, v84, s0
	v_add_co_u32_e64 v84, s[8:9], s2, v120
	v_lshlrev_b32_e32 v93, 16, v87
	s_nop 0
	v_addc_co_u32_e64 v85, s[8:9], 0, v121, s[8:9]
	global_store_short v[84:85], v86, off offset:2560
	v_mul_f32_e32 v84, v119, v93
	s_mov_b32 s2, 0x72000
	v_cvt_pk_bf16_f32 v86, v84, s0
	v_add_co_u32_e64 v84, s[8:9], s2, v120
	v_and_b32_e32 v87, 0xffff0000, v87
	s_nop 0
	v_addc_co_u32_e64 v85, s[8:9], 0, v121, s[8:9]
	global_store_short v[84:85], v86, off offset:3072
	v_mul_f32_e32 v84, v119, v87
	s_mov_b32 s2, 0x74000
	v_cvt_pk_bf16_f32 v86, v84, s0
	v_add_co_u32_e64 v84, s[8:9], s2, v120
	s_mov_b32 s2, 0x77000
	s_nop 0
	v_addc_co_u32_e64 v85, s[8:9], 0, v121, s[8:9]
	global_store_short v[84:85], v86, off offset:3584
	v_lshlrev_b32_e32 v84, 16, v80
	v_and_b32_e32 v85, 0xffff0000, v80
	v_mul_f32_e32 v80, v119, v84
	v_cvt_pk_bf16_f32 v84, v80, s0
	v_add_co_u32_e64 v80, s[8:9], s2, v120
	v_lshlrev_b32_e32 v86, 16, v81
	v_and_b32_e32 v87, 0xffff0000, v81
	v_addc_co_u32_e64 v81, s[8:9], 0, v121, s[8:9]
	global_store_short v[80:81], v84, off
	v_mul_f32_e32 v80, v119, v85
	s_mov_b32 s2, 0x79000
	v_cvt_pk_bf16_f32 v84, v80, s0
	v_add_co_u32_e64 v80, s[8:9], s2, v120
	s_mov_b32 s2, 0x7b000
	s_nop 0
	v_addc_co_u32_e64 v81, s[8:9], 0, v121, s[8:9]
	global_store_short v[80:81], v84, off offset:512
	v_mul_f32_e32 v80, v119, v86
	v_cvt_pk_bf16_f32 v84, v80, s0
	v_add_co_u32_e64 v80, s[8:9], s2, v120
	s_mov_b32 s2, 0x7d000
	s_nop 0
	v_addc_co_u32_e64 v81, s[8:9], 0, v121, s[8:9]
	global_store_short v[80:81], v84, off offset:1024
	v_mul_f32_e32 v80, v119, v87
	v_cvt_pk_bf16_f32 v84, v80, s0
	v_add_co_u32_e64 v80, s[8:9], s2, v120
	v_lshlrev_b32_e32 v88, 16, v82
	s_nop 0
	v_addc_co_u32_e64 v81, s[8:9], 0, v121, s[8:9]
	global_store_short v[80:81], v84, off offset:1536
	v_mul_f32_e32 v80, v119, v88
	s_mov_b32 s2, 0x7f000
	v_cvt_pk_bf16_f32 v84, v80, s0
	v_add_co_u32_e64 v80, s[8:9], s2, v120
	v_and_b32_e32 v82, 0xffff0000, v82
; DI unsigned cvtpk(float lo, float hi) { f32x2_t v = {lo, hi}; bf16x2_t b = __builtin_convertvector(v, bf16x2_t); return __builtin_bit_cast(unsigned, b); }
; DI bf16_t f2bf(float f) { return (bf16_t)(cvtpk(f, f) & 0xffffu); }
; #define UNPK(W_, E_) const float E_[8] = {bflo((W_).x), bfhi((W_).x), bflo((W_).y), bfhi((W_).y), bflo((W_).z), bfhi((W_).z), bflo((W_).w), bfhi((W_).w)}
; #define SSQ8(W_, ACC_) do { UNPK(W_, e_); ACC_ += (e_[0] * e_[0] + e_[1] * e_[1]) + (e_[2] * e_[2] + e_[3] * e_[3]) + (e_[4] * e_[4] + e_[5] * e_[5]) + (e_[6] * e_[6] + e_[7] * e_[7]); } while (0)
; DI void phase_mla_fin(ArgsP a, int tb_, int l, char* shm, int vcu, int G) {
;     ...
;                   for (int j = 0; j < 8; ++j) vo[(size_t)(8 * i + j) * KVLEN] = f2bf(e[j] * rkv); } }
; #pragma unroll
;             for (int i = 0; i < 8; ++i) SSQ8(w[i], ss);
; #pragma unroll
;             for (int i = 0; i < 4; ++i) SSQ8(krp[i], sk);
;             const float rn = rsqrtf((ss * rkv * rkv + sk) * (1.f / 96.f) + EPS);
;             u32x4* o = (u32x4*)(Kb + (bh * KVLEN + pos) * 96);
; #pragma unroll
;             for (int i = 0; i < 8; ++i) { UNPK(w[i], e); const float sc = rn * rkv; u32x4 ow;
;                 ow.x = cvtpk(e[0] * sc * gkn[8 * i], e[1] * sc * gkn[8 * i + 1]); ow.y = cvtpk(e[2] * sc * gkn[8 * i + 2], e[3] * sc * gkn[8 * i + 3]);
;                 ow.z = cvtpk(e[4] * sc * gkn[8 * i + 4], e[5] * sc * gkn[8 * i + 5]); ow.w = cvtpk(e[6] * sc * gkn[8 * i + 6], e[7] * sc * gkn[8 * i + 7]); o[i] = ow; }
;             float cs[16], sn[16];
; #pragma unroll
;             for (int i = 0; i < 4; ++i) { cs[4 * i] = lat ? rc[i].x : 1.f; cs[4 * i + 1] = lat ? rc[i].y : 1.f; cs[4 * i + 2] = lat ? rc[i].z : 1.f; cs[4 * i + 3] = lat ? rc[i].w : 1.f;
	s_nop 0
	v_addc_co_u32_e64 v81, s[8:9], 0, v121, s[8:9]
	global_store_short v[80:81], v84, off offset:2048
	v_mul_f32_e32 v80, v119, v82
	s_mov_b32 s2, 0x81000
	v_cvt_pk_bf16_f32 v82, v80, s0
	v_add_co_u32_e64 v80, s[8:9], s2, v120
	v_lshlrev_b32_e32 v89, 16, v83
	s_nop 0
	v_addc_co_u32_e64 v81, s[8:9], 0, v121, s[8:9]
	global_store_short v[80:81], v82, off offset:2560
	v_mul_f32_e32 v80, v119, v89
	s_mov_b32 s2, 0x83000
	v_cvt_pk_bf16_f32 v82, v80, s0
	v_add_co_u32_e64 v80, s[8:9], s2, v120
	v_and_b32_e32 v83, 0xffff0000, v83
	s_nop 0
	v_addc_co_u32_e64 v81, s[8:9], 0, v121, s[8:9]
	global_store_short v[80:81], v82, off offset:3072
	v_mul_f32_e32 v80, v119, v83
	s_mov_b32 s2, 0x85000
	v_cvt_pk_bf16_f32 v82, v80, s0
	v_add_co_u32_e64 v80, s[8:9], s2, v120
	v_and_b32_e32 v120, 0xffff0000, v76
	s_nop 0
	v_addc_co_u32_e64 v81, s[8:9], 0, v121, s[8:9]
	v_and_b32_e32 v121, 0xffff0000, v77
	v_lshlrev_b32_e32 v123, 16, v77
	v_lshlrev_b32_e32 v122, 16, v76
	v_pk_mul_f32 v[76:77], v[120:121], v[120:121]
	v_and_b32_e32 v111, 0xffff0000, v79
	v_and_b32_e32 v110, 0xffff0000, v78
	v_pk_fma_f32 v[76:77], v[122:123], v[122:123], v[76:77]
	v_lshlrev_b32_e32 v125, 16, v79
	v_lshlrev_b32_e32 v124, 16, v78
	v_pk_mul_f32 v[78:79], v[110:111], v[110:111]
	v_add_f32_e32 v76, v76, v77
	v_pk_fma_f32 v[78:79], v[124:125], v[124:125], v[78:79]
	v_and_b32_e32 v107, 0xffff0000, v69
	v_add_f32_e32 v76, v78, v76
	v_and_b32_e32 v126, 0xffff0000, v70
	v_pk_add_f32 v[128:129], v[78:79], v[76:77] op_sel_hi:[1,0]
	v_lshlrev_b32_e32 v106, 16, v69
	v_mul_f32_e32 v76, v107, v107
	v_lshlrev_b32_e32 v109, 16, v68
	v_lshlrev_b32_e32 v108, 16, v70
	v_pk_mul_f32 v[68:69], v[126:127], v[126:127]
	v_pk_fma_f32 v[76:77], v[106:107], v[106:107], v[76:77] op_sel_hi:[1,1,0]
	v_pk_fma_f32 v[68:69], v[108:109], v[108:109], v[68:69]
	v_lshlrev_b32_e32 v104, 16, v71
	v_pk_add_f32 v[76:77], v[68:69], v[76:77] op_sel:[1,0] op_sel_hi:[0,1]
	v_pk_add_f32 v[134:135], v[68:69], v[76:77]
	v_and_b32_e32 v105, 0xffff0000, v71
	v_mul_f32_e32 v68, v104, v104
	v_and_b32_e32 v101, 0xffff0000, v73
	v_pk_fma_f32 v[136:137], v[104:105], v[104:105], v[68:69] op_sel_hi:[1,1,0]
	v_lshlrev_b32_e32 v100, 16, v73
	v_mul_f32_e32 v68, v101, v101
	v_lshlrev_b32_e32 v103, 16, v72
	v_lshlrev_b32_e32 v102, 16, v74
	v_pk_mul_f32 v[70:71], v[130:131], v[130:131]
	v_pk_fma_f32 v[68:69], v[100:101], v[100:101], v[68:69] op_sel_hi:[1,1,0]
	v_pk_fma_f32 v[70:71], v[102:103], v[102:103], v[70:71]
	v_lshlrev_b32_e32 v98, 16, v75
	v_pk_add_f32 v[68:69], v[70:71], v[68:69] op_sel:[1,0] op_sel_hi:[0,1]
	v_pk_add_f32 v[138:139], v[70:71], v[68:69]
	v_and_b32_e32 v99, 0xffff0000, v75
	v_mul_f32_e32 v68, v98, v98
	v_and_b32_e32 v95, 0xffff0000, v65
	v_pk_fma_f32 v[144:145], v[98:99], v[98:99], v[68:69] op_sel_hi:[1,1,0]
	v_lshlrev_b32_e32 v94, 16, v65
	v_mul_f32_e32 v68, v95, v95
	v_lshlrev_b32_e32 v97, 16, v64
	v_lshlrev_b32_e32 v96, 16, v66
	v_pk_mul_f32 v[64:65], v[132:133], v[132:133]
	v_pk_fma_f32 v[68:69], v[94:95], v[94:95], v[68:69] op_sel_hi:[1,1,0]
	v_pk_fma_f32 v[64:65], v[96:97], v[96:97], v[64:65]
	v_lshlrev_b32_e32 v92, 16, v67
	v_pk_add_f32 v[68:69], v[64:65], v[68:69] op_sel:[1,0] op_sel_hi:[0,1]
	v_pk_add_f32 v[146:147], v[64:65], v[68:69]
	v_and_b32_e32 v93, 0xffff0000, v67
	v_mul_f32_e32 v64, v92, v92
	s_movk_i32 s0, 0x1100
	v_lshlrev_b32_e32 v84, 16, v63
	v_and_b32_e32 v85, 0xffff0000, v63
	v_lshlrev_b32_e32 v74, 16, v59
	v_and_b32_e32 v75, 0xffff0000, v59
	v_and_b32_e32 v59, 0xffff0000, v48
	v_and_b32_e32 v63, 0xffff0000, v49
	global_store_short v[80:81], v82, off offset:3584
	v_pk_fma_f32 v[148:149], v[92:93], v[92:93], v[64:65] op_sel_hi:[1,1,0]
	v_mad_i64_i32 v[64:65], s[4:5], v142, s0, v[188:189]
	v_mov_b64_e32 v[66:67], s[18:19]
	s_movk_i32 s0, 0xc0
	v_lshlrev_b32_e32 v78, 16, v62
	v_and_b32_e32 v79, 0xffff0000, v62
	v_lshlrev_b32_e32 v70, 16, v58
	v_and_b32_e32 v71, 0xffff0000, v58
	v_lshlrev_b32_e32 v76, 16, v52
	v_and_b32_e32 v77, 0xffff0000, v52
	v_lshlrev_b32_e32 v58, 16, v48
	v_lshlrev_b32_e32 v82, 16, v53
	v_and_b32_e32 v83, 0xffff0000, v53
	v_lshlrev_b32_e32 v62, 16, v49
	v_mov_b32_e32 v52, v59
	v_mov_b32_e32 v53, v63
	v_mad_u64_u32 v[68:69], s[4:5], v64, s0, v[66:67]
	v_lshlrev_b32_e32 v66, 16, v60
	v_and_b32_e32 v67, 0xffff0000, v60
	v_lshlrev_b32_e32 v72, 16, v61
	v_and_b32_e32 v73, 0xffff0000, v61
	v_lshlrev_b32_e32 v60, 16, v57
	v_and_b32_e32 v61, 0xffff0000, v57
	v_mov_b32_e32 v48, v58
	v_mov_b32_e32 v49, v62
	v_pk_mul_f32 v[52:53], v[52:53], v[52:53]
	v_and_b32_e32 v81, 0xffff0000, v50
	v_and_b32_e32 v57, 0xffff0000, v51
	v_mad_i32_i24 v69, v65, s0, v69
	v_lshlrev_b32_e32 v64, 16, v56
	v_and_b32_e32 v65, 0xffff0000, v56
	v_pk_fma_f32 v[140:141], v[48:49], v[48:49], v[52:53]
	v_lshlrev_b32_e32 v80, 16, v50
	v_cndmask_b32_e64 v53, 0, v5, s[6:7]
	v_cndmask_b32_e64 v52, 0, v4, s[6:7]
	v_lshlrev_b32_e32 v56, 16, v51
	v_mov_b32_e32 v4, v57
	v_mov_b32_e32 v5, v81
	v_cndmask_b32_e64 v49, 1.0, v1, s[6:7]
	v_cndmask_b32_e64 v48, 1.0, v0, s[6:7]
	v_mov_b32_e32 v0, v56
	v_mov_b32_e32 v1, v80
	v_pk_mul_f32 v[4:5], v[4:5], v[4:5]
	v_mov_b32_e32 v88, 0
	v_lshlrev_b32_e32 v86, 16, v54
	v_and_b32_e32 v87, 0xffff0000, v54
	v_lshlrev_b32_e32 v90, 16, v55
	v_and_b32_e32 v91, 0xffff0000, v55
	v_pk_fma_f32 v[152:153], v[0:1], v[0:1], v[4:5]
	v_cndmask_b32_e64 v51, 1.0, v3, s[6:7]
	v_cndmask_b32_e64 v50, 1.0, v2, s[6:7]
	v_cndmask_b32_e64 v55, 0, v7, s[6:7]
	v_cndmask_b32_e64 v54, 0, v6, s[6:7]
	ds_read_b128 v[0:3], v88 offset:16
	ds_read_b128 v[4:7], v88
	v_pk_mul_f32 v[160:161], v[72:73], v[72:73]
	v_pk_mul_f32 v[162:163], v[78:79], v[78:79]
	v_mov_b32_e32 v136, v160
	v_pk_mov_b32 v[44:45], v[160:161], v[134:135] op_sel:[1,0]
; #define UNPK(W_, E_) const float E_[8] = {bflo((W_).x), bfhi((W_).x), bflo((W_).y), bfhi((W_).y), bflo((W_).z), bfhi((W_).z), bflo((W_).w), bfhi((W_).w)}
; #define SSQ8(W_, ACC_) do { UNPK(W_, e_); ACC_ += (e_[0] * e_[0] + e_[1] * e_[1]) + (e_[2] * e_[2] + e_[3] * e_[3]) + (e_[4] * e_[4] + e_[5] * e_[5]) + (e_[6] * e_[6] + e_[7] * e_[7]); } while (0)
; DI void phase_mla_fin(ArgsP a, int tb_, int l, char* shm, int vcu, int G) {
;     ...
; #pragma unroll
;             for (int i = 0; i < 8; ++i) SSQ8(w[i], ss);
; #pragma unroll
;             for (int i = 0; i < 4; ++i) SSQ8(krp[i], sk);
;             const float rn = rsqrtf((ss * rkv * rkv + sk) * (1.f / 96.f) + EPS);
;             u32x4* o = (u32x4*)(Kb + (bh * KVLEN + pos) * 96);
; #pragma unroll
;             for (int i = 0; i < 8; ++i) { UNPK(w[i], e); const float sc = rn * rkv; u32x4 ow;
	v_mov_b32_e32 v144, v162
	v_pk_add_f32 v[44:45], v[136:137], v[44:45]
	v_pk_mov_b32 v[46:47], v[162:163], v[138:139] op_sel:[1,0]
	v_and_b32_e32 v137, 0xffff0000, v43
	v_pk_add_f32 v[46:47], v[144:145], v[46:47]
	v_lshlrev_b32_e32 v136, 16, v43
	v_mov_b32_e32 v144, v151
	v_mov_b32_e32 v145, v137
	v_mov_b32_e32 v138, v150
	v_mov_b32_e32 v139, v136
	v_pk_mul_f32 v[144:145], v[144:145], v[144:145]
	v_pk_mul_f32 v[164:165], v[84:85], v[84:85]
	v_pk_fma_f32 v[138:139], v[138:139], v[138:139], v[144:145]
	v_and_b32_e32 v145, 0xffff0000, v42
	v_pk_mov_b32 v[134:135], v[164:165], v[146:147] op_sel:[1,0]
	v_lshlrev_b32_e32 v144, 16, v42
	v_mov_b32_e32 v146, v155
	v_mov_b32_e32 v147, v145
	v_mov_b32_e32 v42, v154
	v_mov_b32_e32 v43, v144
	v_pk_mul_f32 v[146:147], v[146:147], v[146:147]
	v_mov_b32_e32 v148, v164
	v_pk_fma_f32 v[42:43], v[42:43], v[42:43], v[146:147]
	v_and_b32_e32 v147, 0xffff0000, v41
	v_lshlrev_b32_e32 v146, 16, v41
	v_mov_b32_e32 v160, v157
	v_mov_b32_e32 v161, v147
	v_pk_add_f32 v[134:135], v[148:149], v[134:135]
	v_mov_b32_e32 v148, v156
	v_mov_b32_e32 v149, v146
	v_pk_mul_f32 v[160:161], v[160:161], v[160:161]
	v_mov_b32_e32 v162, v158
	v_pk_fma_f32 v[148:149], v[148:149], v[148:149], v[160:161]
	v_and_b32_e32 v161, 0xffff0000, v40
	v_lshlrev_b32_e32 v160, 16, v40
	v_mov_b32_e32 v40, v159
	v_mov_b32_e32 v41, v161
	v_pk_mul_f32 v[40:41], v[40:41], v[40:41]
	v_mov_b32_e32 v163, v160
	v_pk_fma_f32 v[40:41], v[162:163], v[162:163], v[40:41]
	v_pk_mul_f32 v[142:143], v[66:67], v[66:67]
	v_pk_add_f32 v[40:41], v[40:41], v[148:149]
	v_mov_b32_e32 v128, v143
	v_pk_add_f32 v[40:41], v[42:43], v[40:41]
	v_mov_b32_e32 v148, v83
	v_pk_add_f32 v[40:41], v[138:139], v[40:41]
	v_mov_b32_e32 v138, v124
	v_pk_add_f32 v[40:41], v[40:41], v[40:41] op_sel_hi:[0,1]
	v_mov_b32_e32 v143, v41
	v_pk_add_f32 v[40:41], v[142:143], v[128:129]
	v_mov_b32_e32 v142, v122
	v_pk_add_f32 v[40:41], v[40:41], v[44:45]
	v_mov_b32_e32 v44, v74
	v_pk_add_f32 v[40:41], v[40:41], v[46:47]
	v_mov_b32_e32 v46, v75
	v_pk_add_f32 v[42:43], v[40:41], v[134:135]
	v_and_b32_e32 v41, 0xffff0000, v39
	v_lshlrev_b32_e32 v40, 16, v39
	v_mov_b32_e32 v47, v41
	v_mov_b32_e32 v45, v40
	v_pk_mul_f32 v[46:47], v[46:47], v[46:47]
	v_mov_b32_e32 v143, v120
	v_pk_fma_f32 v[44:45], v[44:45], v[44:45], v[46:47]
	v_and_b32_e32 v47, 0xffff0000, v38
	v_mov_b32_e32 v120, v123
	v_lshlrev_b32_e32 v46, 16, v38
	v_mov_b32_e32 v122, v71
	v_mov_b32_e32 v123, v47
	v_mov_b32_e32 v38, v70
	v_mov_b32_e32 v39, v46
	v_pk_mul_f32 v[122:123], v[122:123], v[122:123]
	v_mov_b32_e32 v128, v103
	v_pk_fma_f32 v[38:39], v[38:39], v[38:39], v[122:123]
	v_and_b32_e32 v123, 0xffff0000, v37
	v_mov_b32_e32 v129, v131
	v_mov_b32_e32 v103, v130
	v_lshlrev_b32_e32 v122, 16, v37
	v_mov_b32_e32 v130, v61
	v_mov_b32_e32 v131, v123
	v_mov_b32_e32 v134, v109
	v_mov_b32_e32 v135, v127
	v_mov_b32_e32 v109, v126
	v_mov_b32_e32 v126, v60
	v_mov_b32_e32 v127, v122
	v_pk_mul_f32 v[130:131], v[130:131], v[130:131]
	v_mov_b32_e32 v139, v110
	v_pk_fma_f32 v[130:131], v[126:127], v[126:127], v[130:131]
	v_and_b32_e32 v127, 0xffff0000, v36
	v_mov_b32_e32 v110, v125
	v_mov_b32_e32 v124, v97
	v_mov_b32_e32 v125, v133
	v_mov_b32_e32 v97, v132
	v_lshlrev_b32_e32 v126, 16, v36
	v_mov_b32_e32 v132, v65
	v_mov_b32_e32 v133, v127
	v_mov_b32_e32 v36, v64
	v_mov_b32_e32 v37, v126
	v_pk_mul_f32 v[132:133], v[132:133], v[132:133]
	v_mov_b32_e32 v162, v77
	v_pk_fma_f32 v[36:37], v[36:37], v[36:37], v[132:133]
	s_nop 0
	v_pk_add_f32 v[36:37], v[36:37], v[130:131]
	s_nop 0
	v_pk_add_f32 v[36:37], v[38:39], v[36:37]
	v_mov_b32_e32 v38, v90
	v_pk_add_f32 v[36:37], v[44:45], v[36:37]
	v_mov_b32_e32 v44, v82
	v_pk_add_f32 v[130:131], v[42:43], v[36:37]
	v_and_b32_e32 v37, 0xffff0000, v35
	v_lshlrev_b32_e32 v36, 16, v35
	v_mov_b32_e32 v42, v91
	v_mov_b32_e32 v43, v37
	v_mov_b32_e32 v39, v36
	v_pk_mul_f32 v[42:43], v[42:43], v[42:43]
	s_nop 0
	v_pk_fma_f32 v[132:133], v[38:39], v[38:39], v[42:43]
	v_and_b32_e32 v39, 0xffff0000, v34
	v_lshlrev_b32_e32 v38, 16, v34
	v_mov_b32_e32 v42, v87
	v_mov_b32_e32 v43, v39
	v_mov_b32_e32 v34, v86
	v_mov_b32_e32 v35, v38
	v_pk_mul_f32 v[42:43], v[42:43], v[42:43]
	s_nop 0
	v_pk_fma_f32 v[34:35], v[34:35], v[34:35], v[42:43]
	v_and_b32_e32 v43, 0xffff0000, v33
	v_lshlrev_b32_e32 v42, 16, v33
	v_mov_b32_e32 v149, v43
	v_mov_b32_e32 v45, v42
	v_pk_mul_f32 v[148:149], v[148:149], v[148:149]
	s_nop 0
	v_pk_fma_f32 v[148:149], v[44:45], v[44:45], v[148:149]
	v_and_b32_e32 v45, 0xffff0000, v32
	v_lshlrev_b32_e32 v44, 16, v32
	v_mov_b32_e32 v163, v45
	v_mov_b32_e32 v32, v76
	v_mov_b32_e32 v33, v44
	v_pk_mul_f32 v[162:163], v[162:163], v[162:163]
	s_nop 0
	v_pk_fma_f32 v[32:33], v[32:33], v[32:33], v[162:163]
	s_nop 0
	v_pk_add_f32 v[32:33], v[32:33], v[148:149]
	s_nop 0
	v_pk_add_f32 v[32:33], v[34:35], v[32:33]
	v_add_f32_e32 v34, v140, v141
	v_pk_add_f32 v[32:33], v[132:133], v[32:33]
	v_add_f32_e32 v34, v153, v34
	v_pk_add_f32 v[32:33], v[130:131], v[32:33]
	v_add_f32_e32 v34, v152, v34
	v_mul_f32_e32 v33, v33, v119
	v_add_f32_e32 v32, v32, v34
	v_fmac_f32_e32 v32, v119, v33
	v_fmamk_f32 v32, v32, 0x3c2aaaab, v230
	v_cmp_gt_f32_e64 s[8:9], s76, v32
	v_mul_f32_e32 v33, 0x4b800000, v32
	s_nop 0
	v_cndmask_b32_e64 v32, v32, v33, s[8:9]
	v_rsq_f32_e32 v32, v32
	s_nop 0
	v_mul_f32_e32 v33, 0x45800000, v32
	v_cndmask_b32_e64 v32, v32, v33, s[8:9]
	v_mul_f32_e32 v34, v119, v32
	v_pk_mul_f32 v[130:131], v[34:35], v[158:159] op_sel_hi:[0,1]
	s_waitcnt lgkmcnt(0)
; DI unsigned cvtpk(float lo, float hi) { f32x2_t v = {lo, hi}; bf16x2_t b = __builtin_convertvector(v, bf16x2_t); return __builtin_bit_cast(unsigned, b); }
; #define UNPK(W_, E_) const float E_[8] = {bflo((W_).x), bfhi((W_).x), bflo((W_).y), bfhi((W_).y), bflo((W_).z), bfhi((W_).z), bflo((W_).w), bfhi((W_).w)}
; DI void phase_mla_fin(ArgsP a, int tb_, int l, char* shm, int vcu, int G) {
;     ...
;             u32x4* o = (u32x4*)(Kb + (bh * KVLEN + pos) * 96);
; #pragma unroll
;             for (int i = 0; i < 8; ++i) { UNPK(w[i], e); const float sc = rn * rkv; u32x4 ow;
;                 ow.x = cvtpk(e[0] * sc * gkn[8 * i], e[1] * sc * gkn[8 * i + 1]); ow.y = cvtpk(e[2] * sc * gkn[8 * i + 2], e[3] * sc * gkn[8 * i + 3]);
;                 ow.z = cvtpk(e[4] * sc * gkn[8 * i + 4], e[5] * sc * gkn[8 * i + 5]); ow.w = cvtpk(e[6] * sc * gkn[8 * i + 6], e[7] * sc * gkn[8 * i + 7]); o[i] = ow; }
	v_pk_mul_f32 v[4:5], v[130:131], v[4:5]
	v_pk_mul_f32 v[130:131], v[34:35], v[156:157] op_sel_hi:[0,1]
	v_pk_mul_f32 v[6:7], v[130:131], v[6:7]
	v_cvt_pk_bf16_f32 v4, v4, v5
	v_cvt_pk_bf16_f32 v5, v6, v7
	v_pk_mul_f32 v[6:7], v[34:35], v[154:155] op_sel_hi:[0,1]
	v_pk_mul_f32 v[0:1], v[6:7], v[0:1]
	v_pk_mul_f32 v[58:59], v[32:33], v[58:59] op_sel_hi:[0,1]
	v_cvt_pk_bf16_f32 v6, v0, v1
	v_pk_mul_f32 v[0:1], v[34:35], v[150:151] op_sel_hi:[0,1]
	v_pk_mul_f32 v[0:1], v[0:1], v[2:3]
	s_nop 0
	v_cvt_pk_bf16_f32 v7, v0, v1
	global_store_dwordx4 v[68:69], v[4:7], off
	s_nop 1
	ds_read_b128 v[0:3], v88 offset:32
	s_nop 0
	v_pk_mul_f32 v[4:5], v[34:35], v[160:161] op_sel_hi:[0,1]
	v_pk_mul_f32 v[6:7], v[34:35], v[144:145] op_sel_hi:[0,1]
	s_waitcnt lgkmcnt(0)
	v_pk_mul_f32 v[0:1], v[4:5], v[0:1]
	v_pk_mul_f32 v[4:5], v[34:35], v[146:147] op_sel_hi:[0,1]
	v_pk_mul_f32 v[2:3], v[4:5], v[2:3]
	v_cvt_pk_bf16_f32 v0, v0, v1
	v_cvt_pk_bf16_f32 v1, v2, v3
	ds_read_b128 v[2:5], v88 offset:48
	s_waitcnt lgkmcnt(0)
	v_pk_mul_f32 v[2:3], v[6:7], v[2:3]
	v_pk_mul_f32 v[6:7], v[34:35], v[136:137] op_sel_hi:[0,1]
	v_pk_mul_f32 v[4:5], v[6:7], v[4:5]
	v_cvt_pk_bf16_f32 v2, v2, v3
	v_cvt_pk_bf16_f32 v3, v4, v5
	global_store_dwordx4 v[68:69], v[0:3], off offset:16
	s_nop 1
	ds_read_b128 v[0:3], v88 offset:64
	v_pk_mul_f32 v[4:5], v[34:35], v[142:143] op_sel_hi:[0,1]
	v_pk_mul_f32 v[6:7], v[34:35], v[138:139] op_sel_hi:[0,1]
	s_waitcnt lgkmcnt(0)
	v_pk_mul_f32 v[0:1], v[4:5], v[0:1]
	v_pk_mul_f32 v[4:5], v[34:35], v[120:121] op_sel_hi:[0,1]
	v_pk_mul_f32 v[2:3], v[4:5], v[2:3]
	v_cvt_pk_bf16_f32 v0, v0, v1
	v_cvt_pk_bf16_f32 v1, v2, v3
	ds_read_b128 v[2:5], v88 offset:80
	s_waitcnt lgkmcnt(0)
	v_pk_mul_f32 v[2:3], v[6:7], v[2:3]
	v_pk_mul_f32 v[6:7], v[34:35], v[110:111] op_sel_hi:[0,1]
	v_pk_mul_f32 v[4:5], v[6:7], v[4:5]
	v_cvt_pk_bf16_f32 v2, v2, v3
	v_cvt_pk_bf16_f32 v3, v4, v5
	global_store_dwordx4 v[68:69], v[0:3], off offset:32
	s_nop 1
	ds_read_b128 v[0:3], v88 offset:96
	v_pk_mul_f32 v[4:5], v[34:35], v[134:135] op_sel_hi:[0,1]
	v_pk_mul_f32 v[6:7], v[34:35], v[108:109] op_sel_hi:[0,1]
	s_waitcnt lgkmcnt(0)
	v_pk_mul_f32 v[0:1], v[4:5], v[0:1]
	v_pk_mul_f32 v[4:5], v[34:35], v[106:107] op_sel_hi:[0,1]
	v_pk_mul_f32 v[2:3], v[4:5], v[2:3]
	v_cvt_pk_bf16_f32 v0, v0, v1
	v_cvt_pk_bf16_f32 v1, v2, v3
	ds_read_b128 v[2:5], v88 offset:112
	s_waitcnt lgkmcnt(0)
	v_pk_mul_f32 v[2:3], v[6:7], v[2:3]
	v_pk_mul_f32 v[6:7], v[34:35], v[104:105] op_sel_hi:[0,1]
	v_pk_mul_f32 v[4:5], v[6:7], v[4:5]
	v_cvt_pk_bf16_f32 v2, v2, v3
	v_cvt_pk_bf16_f32 v3, v4, v5
	global_store_dwordx4 v[68:69], v[0:3], off offset:48
	s_nop 1
	ds_read_b128 v[0:3], v88 offset:128
	v_pk_mul_f32 v[4:5], v[34:35], v[128:129] op_sel_hi:[0,1]
	v_pk_mul_f32 v[6:7], v[34:35], v[102:103] op_sel_hi:[0,1]
	s_waitcnt lgkmcnt(0)
	v_pk_mul_f32 v[0:1], v[4:5], v[0:1]
	v_pk_mul_f32 v[4:5], v[34:35], v[100:101] op_sel_hi:[0,1]
	v_pk_mul_f32 v[2:3], v[4:5], v[2:3]
	v_cvt_pk_bf16_f32 v0, v0, v1
	v_cvt_pk_bf16_f32 v1, v2, v3
	ds_read_b128 v[2:5], v88 offset:144
	s_waitcnt lgkmcnt(0)
	v_pk_mul_f32 v[2:3], v[6:7], v[2:3]
	v_pk_mul_f32 v[6:7], v[34:35], v[98:99] op_sel_hi:[0,1]
	v_pk_mul_f32 v[4:5], v[6:7], v[4:5]
	v_cvt_pk_bf16_f32 v2, v2, v3
	v_cvt_pk_bf16_f32 v3, v4, v5
	global_store_dwordx4 v[68:69], v[0:3], off offset:64
	s_nop 1
	ds_read_b128 v[0:3], v88 offset:160
	v_pk_mul_f32 v[4:5], v[34:35], v[124:125] op_sel_hi:[0,1]
	v_pk_mul_f32 v[6:7], v[34:35], v[96:97] op_sel_hi:[0,1]
	s_waitcnt lgkmcnt(0)
	v_pk_mul_f32 v[0:1], v[4:5], v[0:1]
	v_pk_mul_f32 v[4:5], v[34:35], v[94:95] op_sel_hi:[0,1]
	v_pk_mul_f32 v[2:3], v[4:5], v[2:3]
	v_cvt_pk_bf16_f32 v0, v0, v1
	v_cvt_pk_bf16_f32 v1, v2, v3
	ds_read_b128 v[2:5], v88 offset:176
	s_waitcnt lgkmcnt(0)
	v_pk_mul_f32 v[2:3], v[6:7], v[2:3]
	v_pk_mul_f32 v[6:7], v[34:35], v[92:93] op_sel_hi:[0,1]
	v_pk_mul_f32 v[4:5], v[6:7], v[4:5]
	v_cvt_pk_bf16_f32 v2, v2, v3
	v_cvt_pk_bf16_f32 v3, v4, v5
	global_store_dwordx4 v[68:69], v[0:3], off offset:80
	s_nop 1
	ds_read_b128 v[0:3], v88 offset:192
	v_pk_mul_f32 v[4:5], v[34:35], v[126:127] op_sel_hi:[0,1]
	v_pk_mul_f32 v[6:7], v[34:35], v[46:47] op_sel_hi:[0,1]
	s_waitcnt lgkmcnt(0)
	v_pk_mul_f32 v[0:1], v[4:5], v[0:1]
	v_pk_mul_f32 v[4:5], v[34:35], v[122:123] op_sel_hi:[0,1]
	v_pk_mul_f32 v[2:3], v[4:5], v[2:3]
	v_cvt_pk_bf16_f32 v0, v0, v1
	v_cvt_pk_bf16_f32 v1, v2, v3
	ds_read_b128 v[2:5], v88 offset:208
	s_waitcnt lgkmcnt(0)
; DI unsigned cvtpk(float lo, float hi) { f32x2_t v = {lo, hi}; bf16x2_t b = __builtin_convertvector(v, bf16x2_t); return __builtin_bit_cast(unsigned, b); }
; #define UNPK(W_, E_) const float E_[8] = {bflo((W_).x), bfhi((W_).x), bflo((W_).y), bfhi((W_).y), bflo((W_).z), bfhi((W_).z), bflo((W_).w), bfhi((W_).w)}
; #define ROPE32(xr) _Pragma("unroll") for (int ax = 0; ax < 2; ++ax) _Pragma("unroll") for (int f = 0; f < 8; ++f) { const float x1 = xr[16 * ax + f], x2 = xr[16 * ax + 8 + f], c = cs[8 * ax + f], sv = sn[8 * ax + f]; xr[16 * ax + f] = x1 * c - x2 * sv; xr[16 * ax + 8 + f] = x2 * c + x1 * sv; }
; DI void phase_mla_fin(ArgsP a, int tb_, int l, char* shm, int vcu, int G) {
;     ...
;             u32x4* o = (u32x4*)(Kb + (bh * KVLEN + pos) * 96);
; #pragma unroll
;             for (int i = 0; i < 8; ++i) { UNPK(w[i], e); const float sc = rn * rkv; u32x4 ow;
;                 ow.x = cvtpk(e[0] * sc * gkn[8 * i], e[1] * sc * gkn[8 * i + 1]); ow.y = cvtpk(e[2] * sc * gkn[8 * i + 2], e[3] * sc * gkn[8 * i + 3]);
;                 ow.z = cvtpk(e[4] * sc * gkn[8 * i + 4], e[5] * sc * gkn[8 * i + 5]); ow.w = cvtpk(e[6] * sc * gkn[8 * i + 6], e[7] * sc * gkn[8 * i + 7]); o[i] = ow; }
;             float cs[16], sn[16];
; #pragma unroll
;             for (int i = 0; i < 4; ++i) { cs[4 * i] = lat ? rc[i].x : 1.f; cs[4 * i + 1] = lat ? rc[i].y : 1.f; cs[4 * i + 2] = lat ? rc[i].z : 1.f; cs[4 * i + 3] = lat ? rc[i].w : 1.f;
;                 sn[4 * i] = lat ? rs[i].x : 0.f; sn[4 * i + 1] = lat ? rs[i].y : 0.f; sn[4 * i + 2] = lat ? rs[i].z : 0.f; sn[4 * i + 3] = lat ? rs[i].w : 0.f; }
;             float xr[32];
; #pragma unroll
;             for (int i = 0; i < 4; ++i) { UNPK(krp[i], e);
; #pragma unroll
;                 for (int j = 0; j < 8; ++j) xr[8 * i + j] = e[j] * rn * gkn[64 + 8 * i + j]; }
;             ROPE32(xr)
	v_pk_mul_f32 v[2:3], v[6:7], v[2:3]
	v_pk_mul_f32 v[6:7], v[34:35], v[40:41] op_sel_hi:[0,1]
	v_pk_mul_f32 v[4:5], v[6:7], v[4:5]
	v_cvt_pk_bf16_f32 v2, v2, v3
	v_cvt_pk_bf16_f32 v3, v4, v5
	global_store_dwordx4 v[68:69], v[0:3], off offset:96
	s_nop 1
	ds_read_b128 v[0:3], v88 offset:224
	v_pk_mul_f32 v[4:5], v[34:35], v[44:45] op_sel_hi:[0,1]
	v_pk_mul_f32 v[6:7], v[34:35], v[38:39] op_sel_hi:[0,1]
	s_waitcnt lgkmcnt(0)
	v_pk_mul_f32 v[0:1], v[4:5], v[0:1]
	v_pk_mul_f32 v[4:5], v[34:35], v[42:43] op_sel_hi:[0,1]
	v_pk_mul_f32 v[2:3], v[4:5], v[2:3]
	v_cvt_pk_bf16_f32 v0, v0, v1
	v_cvt_pk_bf16_f32 v1, v2, v3
	ds_read_b128 v[2:5], v88 offset:240
	s_waitcnt lgkmcnt(0)
	v_pk_mul_f32 v[2:3], v[6:7], v[2:3]
	v_pk_mul_f32 v[6:7], v[34:35], v[36:37] op_sel_hi:[0,1]
	v_pk_mul_f32 v[4:5], v[6:7], v[4:5]
	v_cvt_pk_bf16_f32 v2, v2, v3
	v_cvt_pk_bf16_f32 v3, v4, v5
	global_store_dwordx4 v[68:69], v[0:3], off offset:112
	s_nop 1
	ds_read_b128 v[2:5], v88 offset:256
	s_nop 0
	ds_read_b128 v[34:37], v88 offset:272
	v_pk_mul_f32 v[0:1], v[32:33], v[66:67] op_sel_hi:[0,1]
	ds_read_b128 v[40:43], v88 offset:304
	ds_read_b128 v[44:47], v88 offset:320
	s_waitcnt lgkmcnt(0)
	v_pk_mul_f32 v[2:3], v[0:1], v[2:3]
	v_pk_mul_f32 v[0:1], v[32:33], v[72:73] op_sel_hi:[0,1]
	v_pk_mul_f32 v[0:1], v[0:1], v[4:5]
	v_pk_mul_f32 v[4:5], v[32:33], v[78:79] op_sel_hi:[0,1]
	v_pk_mul_f32 v[6:7], v[4:5], v[34:35]
	v_pk_mul_f32 v[4:5], v[32:33], v[84:85] op_sel_hi:[0,1]
	v_pk_mul_f32 v[4:5], v[4:5], v[36:37]
	ds_read_b128 v[36:39], v88 offset:288
	v_pk_mul_f32 v[34:35], v[32:33], v[64:65] op_sel_hi:[0,1]
	ds_read_b128 v[64:67], v88 offset:336
	s_waitcnt lgkmcnt(0)
	v_pk_mul_f32 v[36:37], v[34:35], v[36:37]
	v_pk_mul_f32 v[34:35], v[32:33], v[60:61] op_sel_hi:[0,1]
	v_pk_mul_f32 v[34:35], v[34:35], v[38:39]
	v_pk_mul_f32 v[38:39], v[32:33], v[70:71] op_sel_hi:[0,1]
	ds_read_b128 v[70:73], v88 offset:352
	v_pk_mul_f32 v[40:41], v[38:39], v[40:41]
	v_pk_mul_f32 v[38:39], v[32:33], v[74:75] op_sel_hi:[0,1]
	v_pk_mul_f32 v[38:39], v[38:39], v[42:43]
	v_pk_mul_f32 v[42:43], v[32:33], v[76:77] op_sel_hi:[0,1]
	v_pk_mul_f32 v[44:45], v[42:43], v[44:45]
	v_pk_mul_f32 v[42:43], v[32:33], v[82:83] op_sel_hi:[0,1]
	v_pk_mul_f32 v[42:43], v[42:43], v[46:47]
	v_pk_mul_f32 v[46:47], v[32:33], v[86:87] op_sel_hi:[0,1]
	v_pk_mul_f32 v[60:61], v[46:47], v[64:65]
	v_pk_mul_f32 v[46:47], v[32:33], v[90:91] op_sel_hi:[0,1]
	v_pk_mul_f32 v[46:47], v[46:47], v[66:67]
	s_waitcnt lgkmcnt(0)
	v_pk_mul_f32 v[66:67], v[58:59], v[70:71]
	v_pk_mul_f32 v[58:59], v[32:33], v[62:63] op_sel_hi:[0,1]
	v_pk_mul_f32 v[62:63], v[58:59], v[72:73]
	ds_read_b128 v[70:73], v88 offset:368
	v_pk_mul_f32 v[58:59], v[32:33], v[80:81] op_sel_hi:[0,1]
	v_pk_mul_f32 v[32:33], v[32:33], v[56:57] op_sel_hi:[0,1]
	s_waitcnt lgkmcnt(0)
	v_pk_mul_f32 v[56:57], v[32:33], v[72:73]
	v_pk_mul_f32 v[32:33], v[24:25], v[36:37]
	v_pk_mul_f32 v[36:37], v[28:29], v[36:37]
	v_pk_mul_f32 v[70:71], v[58:59], v[70:71]
	v_pk_fma_f32 v[58:59], v[24:25], v[2:3], v[36:37] neg_lo:[0,0,1] neg_hi:[0,0,1]
	v_pk_fma_f32 v[64:65], v[28:29], v[2:3], v[32:33]
	v_pk_mul_f32 v[2:3], v[26:27], v[34:35]
	v_pk_mul_f32 v[24:25], v[30:31], v[34:35]
	v_pk_fma_f32 v[74:75], v[30:31], v[0:1], v[2:3]
	v_pk_fma_f32 v[34:35], v[26:27], v[0:1], v[24:25] neg_lo:[0,0,1] neg_hi:[0,0,1]
	v_pk_mul_f32 v[0:1], v[16:17], v[40:41]
	v_pk_mul_f32 v[2:3], v[20:21], v[40:41]
	v_pk_fma_f32 v[78:79], v[20:21], v[6:7], v[0:1]
	v_pk_fma_f32 v[76:77], v[16:17], v[6:7], v[2:3] neg_lo:[0,0,1] neg_hi:[0,0,1]
	v_pk_mul_f32 v[0:1], v[18:19], v[38:39]
	v_pk_mul_f32 v[2:3], v[22:23], v[38:39]
	v_pk_fma_f32 v[80:81], v[22:23], v[4:5], v[0:1]
	v_pk_fma_f32 v[38:39], v[18:19], v[4:5], v[2:3] neg_lo:[0,0,1] neg_hi:[0,0,1]
	v_pk_mul_f32 v[0:1], v[8:9], v[66:67]
	v_pk_mul_f32 v[2:3], v[12:13], v[66:67]
	v_pk_fma_f32 v[66:67], v[12:13], v[44:45], v[0:1]
	v_pk_fma_f32 v[36:37], v[8:9], v[44:45], v[2:3] neg_lo:[0,0,1] neg_hi:[0,0,1]
	v_pk_mul_f32 v[0:1], v[10:11], v[62:63]
	v_pk_mul_f32 v[2:3], v[14:15], v[62:63]
	s_nop 0
	v_pk_fma_f32 v[32:33], v[10:11], v[42:43], v[2:3] neg_lo:[0,0,1] neg_hi:[0,0,1]
	v_pk_fma_f32 v[42:43], v[14:15], v[42:43], v[0:1]
	v_pk_mul_f32 v[0:1], v[48:49], v[70:71]
	v_pk_mul_f32 v[2:3], v[52:53], v[70:71]
	s_nop 0
	v_pk_fma_f32 v[44:45], v[48:49], v[60:61], v[2:3] neg_lo:[0,0,1] neg_hi:[0,0,1]
	v_pk_fma_f32 v[48:49], v[52:53], v[60:61], v[0:1]
	v_pk_mul_f32 v[0:1], v[50:51], v[56:57]
	v_pk_mul_f32 v[2:3], v[54:55], v[56:57]
	v_pk_fma_f32 v[40:41], v[54:55], v[46:47], v[0:1]
	v_pk_fma_f32 v[50:51], v[50:51], v[46:47], v[2:3] neg_lo:[0,0,1] neg_hi:[0,0,1]
